# adaLN GEMV K loop hand-pipelined: saddr loads, 64 rows in flight, 3 fmac per row (no pair shuffles)
# speedup vs baseline: 1.0161x; 1.0017x over previous
.LBB0_23:
	s_mul_hi_i32 s4, s55, 0x2aaaaaab
	s_lshr_b32 s5, s4, 31
	s_ashr_i32 s4, s4, 5
	s_add_i32 s14, s4, s5
	s_mul_i32 s4, s14, 0xc0
	s_sub_i32 s4, s55, s4
	s_ashr_i32 s15, s14, 31
	s_lshl_b32 s16, s4, 6
	s_lshl_b64 s[4:5], s[14:15], 11
	s_add_u32 s4, s4, s7
	s_addc_u32 s5, s5, s21
	s_mul_i32 s5, s5, 0xc000
	s_mul_hi_u32 s15, s4, 0xc000
	s_add_i32 s15, s15, s5
	s_mul_i32 s4, s4, 0xc000
	v_or_b32_e32 v8, s16, v6
	s_waitcnt lgkmcnt(0)
	s_add_u32 s4, s10, s4
	s_addc_u32 s5, s11, s15
	v_lshlrev_b32_e32 v172, 2, v8
	v_ashrrev_i32_e32 v9, 31, v8
	v_lshl_add_u64 v[8:9], v[8:9], 2, s[4:5]
	s_mov_b64 s[18:19], 0
	s_mov_b32 s15, s22
	v_mov_b32_e32 v7, 0
	v_mov_b32_e32 v10, 0
	v_mov_b32_e32 v11, v3
.LBB0_24:
	s_mov_b64 s[18:19], s[4:5]
	s_mov_b32 s17, 3
	global_load_dword v108, v172, s[18:19]
	s_add_u32 s18, s18, 0xc000
	s_addc_u32 s19, s19, 0
	global_load_dword v109, v172, s[18:19]
	s_add_u32 s18, s18, 0xc000
	s_addc_u32 s19, s19, 0
	global_load_dword v110, v172, s[18:19]
	s_add_u32 s18, s18, 0xc000
	s_addc_u32 s19, s19, 0
	global_load_dword v111, v172, s[18:19]
	s_add_u32 s18, s18, 0xc000
	s_addc_u32 s19, s19, 0
	global_load_dword v112, v172, s[18:19]
	s_add_u32 s18, s18, 0xc000
	s_addc_u32 s19, s19, 0
	global_load_dword v113, v172, s[18:19]
	s_add_u32 s18, s18, 0xc000
	s_addc_u32 s19, s19, 0
	global_load_dword v114, v172, s[18:19]
	s_add_u32 s18, s18, 0xc000
	s_addc_u32 s19, s19, 0
	global_load_dword v115, v172, s[18:19]
	s_add_u32 s18, s18, 0xc000
	s_addc_u32 s19, s19, 0
	global_load_dword v116, v172, s[18:19]
	s_add_u32 s18, s18, 0xc000
	s_addc_u32 s19, s19, 0
	global_load_dword v117, v172, s[18:19]
	s_add_u32 s18, s18, 0xc000
	s_addc_u32 s19, s19, 0
	global_load_dword v118, v172, s[18:19]
	s_add_u32 s18, s18, 0xc000
	s_addc_u32 s19, s19, 0
	global_load_dword v119, v172, s[18:19]
	s_add_u32 s18, s18, 0xc000
	s_addc_u32 s19, s19, 0
	global_load_dword v120, v172, s[18:19]
	s_add_u32 s18, s18, 0xc000
	s_addc_u32 s19, s19, 0
	global_load_dword v121, v172, s[18:19]
	s_add_u32 s18, s18, 0xc000
	s_addc_u32 s19, s19, 0
	global_load_dword v122, v172, s[18:19]
	s_add_u32 s18, s18, 0xc000
	s_addc_u32 s19, s19, 0
	global_load_dword v123, v172, s[18:19]
	s_add_u32 s18, s18, 0xc000
	s_addc_u32 s19, s19, 0
	global_load_dword v124, v172, s[18:19]
	s_add_u32 s18, s18, 0xc000
	s_addc_u32 s19, s19, 0
	global_load_dword v125, v172, s[18:19]
	s_add_u32 s18, s18, 0xc000
	s_addc_u32 s19, s19, 0
	global_load_dword v126, v172, s[18:19]
	s_add_u32 s18, s18, 0xc000
	s_addc_u32 s19, s19, 0
	global_load_dword v127, v172, s[18:19]
	s_add_u32 s18, s18, 0xc000
	s_addc_u32 s19, s19, 0
	global_load_dword v128, v172, s[18:19]
	s_add_u32 s18, s18, 0xc000
	s_addc_u32 s19, s19, 0
	global_load_dword v129, v172, s[18:19]
	s_add_u32 s18, s18, 0xc000
	s_addc_u32 s19, s19, 0
	global_load_dword v130, v172, s[18:19]
	s_add_u32 s18, s18, 0xc000
	s_addc_u32 s19, s19, 0
	global_load_dword v131, v172, s[18:19]
	s_add_u32 s18, s18, 0xc000
	s_addc_u32 s19, s19, 0
	global_load_dword v132, v172, s[18:19]
	s_add_u32 s18, s18, 0xc000
	s_addc_u32 s19, s19, 0
	global_load_dword v133, v172, s[18:19]
	s_add_u32 s18, s18, 0xc000
	s_addc_u32 s19, s19, 0
	global_load_dword v134, v172, s[18:19]
	s_add_u32 s18, s18, 0xc000
	s_addc_u32 s19, s19, 0
	global_load_dword v135, v172, s[18:19]
	s_add_u32 s18, s18, 0xc000
	s_addc_u32 s19, s19, 0
	global_load_dword v136, v172, s[18:19]
	s_add_u32 s18, s18, 0xc000
	s_addc_u32 s19, s19, 0
	global_load_dword v137, v172, s[18:19]
	s_add_u32 s18, s18, 0xc000
	s_addc_u32 s19, s19, 0
	global_load_dword v138, v172, s[18:19]
	s_add_u32 s18, s18, 0xc000
	s_addc_u32 s19, s19, 0
	global_load_dword v139, v172, s[18:19]
	s_add_u32 s18, s18, 0xc000
	s_addc_u32 s19, s19, 0
.Lada_loop:
	global_load_dword v140, v172, s[18:19]
	s_add_u32 s18, s18, 0xc000
	s_addc_u32 s19, s19, 0
	global_load_dword v141, v172, s[18:19]
	s_add_u32 s18, s18, 0xc000
	s_addc_u32 s19, s19, 0
	global_load_dword v142, v172, s[18:19]
	s_add_u32 s18, s18, 0xc000
	s_addc_u32 s19, s19, 0
	global_load_dword v143, v172, s[18:19]
	s_add_u32 s18, s18, 0xc000
	s_addc_u32 s19, s19, 0
	global_load_dword v144, v172, s[18:19]
	s_add_u32 s18, s18, 0xc000
	s_addc_u32 s19, s19, 0
	global_load_dword v145, v172, s[18:19]
	s_add_u32 s18, s18, 0xc000
	s_addc_u32 s19, s19, 0
	global_load_dword v146, v172, s[18:19]
	s_add_u32 s18, s18, 0xc000
	s_addc_u32 s19, s19, 0
	global_load_dword v147, v172, s[18:19]
	s_add_u32 s18, s18, 0xc000
	s_addc_u32 s19, s19, 0
	global_load_dword v148, v172, s[18:19]
	s_add_u32 s18, s18, 0xc000
	s_addc_u32 s19, s19, 0
	global_load_dword v149, v172, s[18:19]
	s_add_u32 s18, s18, 0xc000
	s_addc_u32 s19, s19, 0
	global_load_dword v150, v172, s[18:19]
	s_add_u32 s18, s18, 0xc000
	s_addc_u32 s19, s19, 0
	global_load_dword v151, v172, s[18:19]
	s_add_u32 s18, s18, 0xc000
	s_addc_u32 s19, s19, 0
	global_load_dword v152, v172, s[18:19]
	s_add_u32 s18, s18, 0xc000
	s_addc_u32 s19, s19, 0
	global_load_dword v153, v172, s[18:19]
	s_add_u32 s18, s18, 0xc000
	s_addc_u32 s19, s19, 0
	global_load_dword v154, v172, s[18:19]
	s_add_u32 s18, s18, 0xc000
	s_addc_u32 s19, s19, 0
	global_load_dword v155, v172, s[18:19]
	s_add_u32 s18, s18, 0xc000
	s_addc_u32 s19, s19, 0
	global_load_dword v156, v172, s[18:19]
	s_add_u32 s18, s18, 0xc000
	s_addc_u32 s19, s19, 0
	global_load_dword v157, v172, s[18:19]
	s_add_u32 s18, s18, 0xc000
	s_addc_u32 s19, s19, 0
	global_load_dword v158, v172, s[18:19]
	s_add_u32 s18, s18, 0xc000
	s_addc_u32 s19, s19, 0
	global_load_dword v159, v172, s[18:19]
	s_add_u32 s18, s18, 0xc000
	s_addc_u32 s19, s19, 0
	global_load_dword v160, v172, s[18:19]
	s_add_u32 s18, s18, 0xc000
	s_addc_u32 s19, s19, 0
	global_load_dword v161, v172, s[18:19]
	s_add_u32 s18, s18, 0xc000
	s_addc_u32 s19, s19, 0
	global_load_dword v162, v172, s[18:19]
	s_add_u32 s18, s18, 0xc000
	s_addc_u32 s19, s19, 0
	global_load_dword v163, v172, s[18:19]
	s_add_u32 s18, s18, 0xc000
	s_addc_u32 s19, s19, 0
	global_load_dword v164, v172, s[18:19]
	s_add_u32 s18, s18, 0xc000
	s_addc_u32 s19, s19, 0
	global_load_dword v165, v172, s[18:19]
	s_add_u32 s18, s18, 0xc000
	s_addc_u32 s19, s19, 0
	global_load_dword v166, v172, s[18:19]
	s_add_u32 s18, s18, 0xc000
	s_addc_u32 s19, s19, 0
	global_load_dword v167, v172, s[18:19]
	s_add_u32 s18, s18, 0xc000
	s_addc_u32 s19, s19, 0
	global_load_dword v168, v172, s[18:19]
	s_add_u32 s18, s18, 0xc000
	s_addc_u32 s19, s19, 0
	global_load_dword v169, v172, s[18:19]
	s_add_u32 s18, s18, 0xc000
	s_addc_u32 s19, s19, 0
	global_load_dword v170, v172, s[18:19]
	s_add_u32 s18, s18, 0xc000
	s_addc_u32 s19, s19, 0
	global_load_dword v171, v172, s[18:19]
	s_add_u32 s18, s18, 0xc000
	s_addc_u32 s19, s19, 0
	v_mov_b32_e32 v173, s15
	ds_read_b128 v[12:15], v173 offset:0
	ds_read_b128 v[16:19], v173 offset:16
	ds_read_b128 v[20:23], v173 offset:32
	ds_read_b128 v[24:27], v173 offset:48
	ds_read_b128 v[28:31], v173 offset:64
	ds_read_b128 v[32:35], v173 offset:80
	ds_read_b128 v[36:39], v173 offset:96
	ds_read_b128 v[40:43], v173 offset:112
	ds_read_b128 v[44:47], v173 offset:8192
	ds_read_b128 v[48:51], v173 offset:8208
	ds_read_b128 v[52:55], v173 offset:8224
	ds_read_b128 v[56:59], v173 offset:8240
	ds_read_b128 v[60:63], v173 offset:8256
	ds_read_b128 v[64:67], v173 offset:8272
	ds_read_b128 v[68:71], v173 offset:8288
	ds_read_b128 v[72:75], v173 offset:8304
	ds_read_b128 v[76:79], v173 offset:16384
	ds_read_b128 v[80:83], v173 offset:16400
	ds_read_b128 v[84:87], v173 offset:16416
	ds_read_b128 v[88:91], v173 offset:16432
	ds_read_b128 v[92:95], v173 offset:16448
	ds_read_b128 v[96:99], v173 offset:16464
	ds_read_b128 v[100:103], v173 offset:16480
	ds_read_b128 v[104:107], v173 offset:16496
	s_addk_i32 s15, 0x80
	s_waitcnt lgkmcnt(0)
	s_waitcnt vmcnt(63)
	v_fmac_f32_e32 v10, v108, v12
	v_fmac_f32_e32 v11, v108, v44
	v_fmac_f32_e32 v7, v108, v76
	s_waitcnt vmcnt(62)
	v_fmac_f32_e32 v10, v109, v13
	v_fmac_f32_e32 v11, v109, v45
	v_fmac_f32_e32 v7, v109, v77
	s_waitcnt vmcnt(61)
	v_fmac_f32_e32 v10, v110, v14
	v_fmac_f32_e32 v11, v110, v46
	v_fmac_f32_e32 v7, v110, v78
	s_waitcnt vmcnt(60)
	v_fmac_f32_e32 v10, v111, v15
	v_fmac_f32_e32 v11, v111, v47
	v_fmac_f32_e32 v7, v111, v79
	s_waitcnt vmcnt(59)
	v_fmac_f32_e32 v10, v112, v16
	v_fmac_f32_e32 v11, v112, v48
	v_fmac_f32_e32 v7, v112, v80
	s_waitcnt vmcnt(58)
	v_fmac_f32_e32 v10, v113, v17
	v_fmac_f32_e32 v11, v113, v49
	v_fmac_f32_e32 v7, v113, v81
	s_waitcnt vmcnt(57)
	v_fmac_f32_e32 v10, v114, v18
	v_fmac_f32_e32 v11, v114, v50
	v_fmac_f32_e32 v7, v114, v82
	s_waitcnt vmcnt(56)
	v_fmac_f32_e32 v10, v115, v19
	v_fmac_f32_e32 v11, v115, v51
	v_fmac_f32_e32 v7, v115, v83
	s_waitcnt vmcnt(55)
	v_fmac_f32_e32 v10, v116, v20
	v_fmac_f32_e32 v11, v116, v52
	v_fmac_f32_e32 v7, v116, v84
	s_waitcnt vmcnt(54)
	v_fmac_f32_e32 v10, v117, v21
	v_fmac_f32_e32 v11, v117, v53
	v_fmac_f32_e32 v7, v117, v85
	s_waitcnt vmcnt(53)
	v_fmac_f32_e32 v10, v118, v22
	v_fmac_f32_e32 v11, v118, v54
	v_fmac_f32_e32 v7, v118, v86
	s_waitcnt vmcnt(52)
	v_fmac_f32_e32 v10, v119, v23
	v_fmac_f32_e32 v11, v119, v55
	v_fmac_f32_e32 v7, v119, v87
	s_waitcnt vmcnt(51)
	v_fmac_f32_e32 v10, v120, v24
	v_fmac_f32_e32 v11, v120, v56
	v_fmac_f32_e32 v7, v120, v88
	s_waitcnt vmcnt(50)
	v_fmac_f32_e32 v10, v121, v25
	v_fmac_f32_e32 v11, v121, v57
	v_fmac_f32_e32 v7, v121, v89
	s_waitcnt vmcnt(49)
	v_fmac_f32_e32 v10, v122, v26
	v_fmac_f32_e32 v11, v122, v58
	v_fmac_f32_e32 v7, v122, v90
	s_waitcnt vmcnt(48)
	v_fmac_f32_e32 v10, v123, v27
	v_fmac_f32_e32 v11, v123, v59
	v_fmac_f32_e32 v7, v123, v91
	s_waitcnt vmcnt(47)
	v_fmac_f32_e32 v10, v124, v28
	v_fmac_f32_e32 v11, v124, v60
	v_fmac_f32_e32 v7, v124, v92
	s_waitcnt vmcnt(46)
	v_fmac_f32_e32 v10, v125, v29
	v_fmac_f32_e32 v11, v125, v61
	v_fmac_f32_e32 v7, v125, v93
	s_waitcnt vmcnt(45)
	v_fmac_f32_e32 v10, v126, v30
	v_fmac_f32_e32 v11, v126, v62
	v_fmac_f32_e32 v7, v126, v94
	s_waitcnt vmcnt(44)
	v_fmac_f32_e32 v10, v127, v31
	v_fmac_f32_e32 v11, v127, v63
	v_fmac_f32_e32 v7, v127, v95
	s_waitcnt vmcnt(43)
	v_fmac_f32_e32 v10, v128, v32
	v_fmac_f32_e32 v11, v128, v64
	v_fmac_f32_e32 v7, v128, v96
	s_waitcnt vmcnt(42)
	v_fmac_f32_e32 v10, v129, v33
	v_fmac_f32_e32 v11, v129, v65
	v_fmac_f32_e32 v7, v129, v97
	s_waitcnt vmcnt(41)
	v_fmac_f32_e32 v10, v130, v34
	v_fmac_f32_e32 v11, v130, v66
	v_fmac_f32_e32 v7, v130, v98
	s_waitcnt vmcnt(40)
	v_fmac_f32_e32 v10, v131, v35
	v_fmac_f32_e32 v11, v131, v67
	v_fmac_f32_e32 v7, v131, v99
	s_waitcnt vmcnt(39)
	v_fmac_f32_e32 v10, v132, v36
	v_fmac_f32_e32 v11, v132, v68
	v_fmac_f32_e32 v7, v132, v100
	s_waitcnt vmcnt(38)
	v_fmac_f32_e32 v10, v133, v37
	v_fmac_f32_e32 v11, v133, v69
	v_fmac_f32_e32 v7, v133, v101
	s_waitcnt vmcnt(37)
	v_fmac_f32_e32 v10, v134, v38
	v_fmac_f32_e32 v11, v134, v70
	v_fmac_f32_e32 v7, v134, v102
	s_waitcnt vmcnt(36)
	v_fmac_f32_e32 v10, v135, v39
	v_fmac_f32_e32 v11, v135, v71
	v_fmac_f32_e32 v7, v135, v103
	s_waitcnt vmcnt(35)
	v_fmac_f32_e32 v10, v136, v40
	v_fmac_f32_e32 v11, v136, v72
	v_fmac_f32_e32 v7, v136, v104
	s_waitcnt vmcnt(34)
	v_fmac_f32_e32 v10, v137, v41
	v_fmac_f32_e32 v11, v137, v73
	v_fmac_f32_e32 v7, v137, v105
	s_waitcnt vmcnt(33)
	v_fmac_f32_e32 v10, v138, v42
	v_fmac_f32_e32 v11, v138, v74
	v_fmac_f32_e32 v7, v138, v106
	s_waitcnt vmcnt(32)
	v_fmac_f32_e32 v10, v139, v43
	v_fmac_f32_e32 v11, v139, v75
	v_fmac_f32_e32 v7, v139, v107
	global_load_dword v108, v172, s[18:19]
	s_add_u32 s18, s18, 0xc000
	s_addc_u32 s19, s19, 0
	global_load_dword v109, v172, s[18:19]
	s_add_u32 s18, s18, 0xc000
	s_addc_u32 s19, s19, 0
	global_load_dword v110, v172, s[18:19]
	s_add_u32 s18, s18, 0xc000
	s_addc_u32 s19, s19, 0
	global_load_dword v111, v172, s[18:19]
	s_add_u32 s18, s18, 0xc000
	s_addc_u32 s19, s19, 0
	global_load_dword v112, v172, s[18:19]
	s_add_u32 s18, s18, 0xc000
	s_addc_u32 s19, s19, 0
	global_load_dword v113, v172, s[18:19]
	s_add_u32 s18, s18, 0xc000
	s_addc_u32 s19, s19, 0
	global_load_dword v114, v172, s[18:19]
	s_add_u32 s18, s18, 0xc000
	s_addc_u32 s19, s19, 0
	global_load_dword v115, v172, s[18:19]
	s_add_u32 s18, s18, 0xc000
	s_addc_u32 s19, s19, 0
	global_load_dword v116, v172, s[18:19]
	s_add_u32 s18, s18, 0xc000
	s_addc_u32 s19, s19, 0
	global_load_dword v117, v172, s[18:19]
	s_add_u32 s18, s18, 0xc000
	s_addc_u32 s19, s19, 0
	global_load_dword v118, v172, s[18:19]
	s_add_u32 s18, s18, 0xc000
	s_addc_u32 s19, s19, 0
	global_load_dword v119, v172, s[18:19]
	s_add_u32 s18, s18, 0xc000
	s_addc_u32 s19, s19, 0
	global_load_dword v120, v172, s[18:19]
	s_add_u32 s18, s18, 0xc000
	s_addc_u32 s19, s19, 0
	global_load_dword v121, v172, s[18:19]
	s_add_u32 s18, s18, 0xc000
	s_addc_u32 s19, s19, 0
	global_load_dword v122, v172, s[18:19]
	s_add_u32 s18, s18, 0xc000
	s_addc_u32 s19, s19, 0
	global_load_dword v123, v172, s[18:19]
	s_add_u32 s18, s18, 0xc000
	s_addc_u32 s19, s19, 0
	global_load_dword v124, v172, s[18:19]
	s_add_u32 s18, s18, 0xc000
	s_addc_u32 s19, s19, 0
	global_load_dword v125, v172, s[18:19]
	s_add_u32 s18, s18, 0xc000
	s_addc_u32 s19, s19, 0
	global_load_dword v126, v172, s[18:19]
	s_add_u32 s18, s18, 0xc000
	s_addc_u32 s19, s19, 0
	global_load_dword v127, v172, s[18:19]
	s_add_u32 s18, s18, 0xc000
	s_addc_u32 s19, s19, 0
	global_load_dword v128, v172, s[18:19]
	s_add_u32 s18, s18, 0xc000
	s_addc_u32 s19, s19, 0
	global_load_dword v129, v172, s[18:19]
	s_add_u32 s18, s18, 0xc000
	s_addc_u32 s19, s19, 0
	global_load_dword v130, v172, s[18:19]
	s_add_u32 s18, s18, 0xc000
	s_addc_u32 s19, s19, 0
	global_load_dword v131, v172, s[18:19]
	s_add_u32 s18, s18, 0xc000
	s_addc_u32 s19, s19, 0
	global_load_dword v132, v172, s[18:19]
	s_add_u32 s18, s18, 0xc000
	s_addc_u32 s19, s19, 0
	global_load_dword v133, v172, s[18:19]
	s_add_u32 s18, s18, 0xc000
	s_addc_u32 s19, s19, 0
	global_load_dword v134, v172, s[18:19]
	s_add_u32 s18, s18, 0xc000
	s_addc_u32 s19, s19, 0
	global_load_dword v135, v172, s[18:19]
	s_add_u32 s18, s18, 0xc000
	s_addc_u32 s19, s19, 0
	global_load_dword v136, v172, s[18:19]
	s_add_u32 s18, s18, 0xc000
	s_addc_u32 s19, s19, 0
	global_load_dword v137, v172, s[18:19]
	s_add_u32 s18, s18, 0xc000
	s_addc_u32 s19, s19, 0
	global_load_dword v138, v172, s[18:19]
	s_add_u32 s18, s18, 0xc000
	s_addc_u32 s19, s19, 0
	global_load_dword v139, v172, s[18:19]
	s_add_u32 s18, s18, 0xc000
	s_addc_u32 s19, s19, 0
	v_mov_b32_e32 v173, s15
	ds_read_b128 v[12:15], v173 offset:0
	ds_read_b128 v[16:19], v173 offset:16
	ds_read_b128 v[20:23], v173 offset:32
	ds_read_b128 v[24:27], v173 offset:48
	ds_read_b128 v[28:31], v173 offset:64
	ds_read_b128 v[32:35], v173 offset:80
	ds_read_b128 v[36:39], v173 offset:96
	ds_read_b128 v[40:43], v173 offset:112
	ds_read_b128 v[44:47], v173 offset:8192
	ds_read_b128 v[48:51], v173 offset:8208
	ds_read_b128 v[52:55], v173 offset:8224
	ds_read_b128 v[56:59], v173 offset:8240
	ds_read_b128 v[60:63], v173 offset:8256
	ds_read_b128 v[64:67], v173 offset:8272
	ds_read_b128 v[68:71], v173 offset:8288
	ds_read_b128 v[72:75], v173 offset:8304
	ds_read_b128 v[76:79], v173 offset:16384
	ds_read_b128 v[80:83], v173 offset:16400
	ds_read_b128 v[84:87], v173 offset:16416
	ds_read_b128 v[88:91], v173 offset:16432
	ds_read_b128 v[92:95], v173 offset:16448
	ds_read_b128 v[96:99], v173 offset:16464
	ds_read_b128 v[100:103], v173 offset:16480
	ds_read_b128 v[104:107], v173 offset:16496
	s_addk_i32 s15, 0x80
	s_waitcnt lgkmcnt(0)
	s_waitcnt vmcnt(63)
	v_fmac_f32_e32 v10, v140, v12
	v_fmac_f32_e32 v11, v140, v44
	v_fmac_f32_e32 v7, v140, v76
	s_waitcnt vmcnt(62)
	v_fmac_f32_e32 v10, v141, v13
	v_fmac_f32_e32 v11, v141, v45
	v_fmac_f32_e32 v7, v141, v77
	s_waitcnt vmcnt(61)
	v_fmac_f32_e32 v10, v142, v14
	v_fmac_f32_e32 v11, v142, v46
	v_fmac_f32_e32 v7, v142, v78
	s_waitcnt vmcnt(60)
	v_fmac_f32_e32 v10, v143, v15
	v_fmac_f32_e32 v11, v143, v47
	v_fmac_f32_e32 v7, v143, v79
	s_waitcnt vmcnt(59)
	v_fmac_f32_e32 v10, v144, v16
	v_fmac_f32_e32 v11, v144, v48
	v_fmac_f32_e32 v7, v144, v80
	s_waitcnt vmcnt(58)
	v_fmac_f32_e32 v10, v145, v17
	v_fmac_f32_e32 v11, v145, v49
	v_fmac_f32_e32 v7, v145, v81
	s_waitcnt vmcnt(57)
	v_fmac_f32_e32 v10, v146, v18
	v_fmac_f32_e32 v11, v146, v50
	v_fmac_f32_e32 v7, v146, v82
	s_waitcnt vmcnt(56)
	v_fmac_f32_e32 v10, v147, v19
	v_fmac_f32_e32 v11, v147, v51
	v_fmac_f32_e32 v7, v147, v83
	s_waitcnt vmcnt(55)
	v_fmac_f32_e32 v10, v148, v20
	v_fmac_f32_e32 v11, v148, v52
	v_fmac_f32_e32 v7, v148, v84
	s_waitcnt vmcnt(54)
	v_fmac_f32_e32 v10, v149, v21
	v_fmac_f32_e32 v11, v149, v53
	v_fmac_f32_e32 v7, v149, v85
	s_waitcnt vmcnt(53)
	v_fmac_f32_e32 v10, v150, v22
	v_fmac_f32_e32 v11, v150, v54
	v_fmac_f32_e32 v7, v150, v86
	s_waitcnt vmcnt(52)
	v_fmac_f32_e32 v10, v151, v23
	v_fmac_f32_e32 v11, v151, v55
	v_fmac_f32_e32 v7, v151, v87
	s_waitcnt vmcnt(51)
	v_fmac_f32_e32 v10, v152, v24
	v_fmac_f32_e32 v11, v152, v56
	v_fmac_f32_e32 v7, v152, v88
	s_waitcnt vmcnt(50)
	v_fmac_f32_e32 v10, v153, v25
	v_fmac_f32_e32 v11, v153, v57
	v_fmac_f32_e32 v7, v153, v89
	s_waitcnt vmcnt(49)
	v_fmac_f32_e32 v10, v154, v26
	v_fmac_f32_e32 v11, v154, v58
	v_fmac_f32_e32 v7, v154, v90
	s_waitcnt vmcnt(48)
	v_fmac_f32_e32 v10, v155, v27
	v_fmac_f32_e32 v11, v155, v59
	v_fmac_f32_e32 v7, v155, v91
	s_waitcnt vmcnt(47)
	v_fmac_f32_e32 v10, v156, v28
	v_fmac_f32_e32 v11, v156, v60
	v_fmac_f32_e32 v7, v156, v92
	s_waitcnt vmcnt(46)
	v_fmac_f32_e32 v10, v157, v29
	v_fmac_f32_e32 v11, v157, v61
	v_fmac_f32_e32 v7, v157, v93
	s_waitcnt vmcnt(45)
	v_fmac_f32_e32 v10, v158, v30
	v_fmac_f32_e32 v11, v158, v62
	v_fmac_f32_e32 v7, v158, v94
	s_waitcnt vmcnt(44)
	v_fmac_f32_e32 v10, v159, v31
	v_fmac_f32_e32 v11, v159, v63
	v_fmac_f32_e32 v7, v159, v95
	s_waitcnt vmcnt(43)
	v_fmac_f32_e32 v10, v160, v32
	v_fmac_f32_e32 v11, v160, v64
	v_fmac_f32_e32 v7, v160, v96
	s_waitcnt vmcnt(42)
	v_fmac_f32_e32 v10, v161, v33
	v_fmac_f32_e32 v11, v161, v65
	v_fmac_f32_e32 v7, v161, v97
	s_waitcnt vmcnt(41)
	v_fmac_f32_e32 v10, v162, v34
	v_fmac_f32_e32 v11, v162, v66
	v_fmac_f32_e32 v7, v162, v98
	s_waitcnt vmcnt(40)
	v_fmac_f32_e32 v10, v163, v35
	v_fmac_f32_e32 v11, v163, v67
	v_fmac_f32_e32 v7, v163, v99
	s_waitcnt vmcnt(39)
	v_fmac_f32_e32 v10, v164, v36
	v_fmac_f32_e32 v11, v164, v68
	v_fmac_f32_e32 v7, v164, v100
	s_waitcnt vmcnt(38)
	v_fmac_f32_e32 v10, v165, v37
	v_fmac_f32_e32 v11, v165, v69
	v_fmac_f32_e32 v7, v165, v101
	s_waitcnt vmcnt(37)
	v_fmac_f32_e32 v10, v166, v38
	v_fmac_f32_e32 v11, v166, v70
	v_fmac_f32_e32 v7, v166, v102
	s_waitcnt vmcnt(36)
	v_fmac_f32_e32 v10, v167, v39
	v_fmac_f32_e32 v11, v167, v71
	v_fmac_f32_e32 v7, v167, v103
	s_waitcnt vmcnt(35)
	v_fmac_f32_e32 v10, v168, v40
	v_fmac_f32_e32 v11, v168, v72
	v_fmac_f32_e32 v7, v168, v104
	s_waitcnt vmcnt(34)
	v_fmac_f32_e32 v10, v169, v41
	v_fmac_f32_e32 v11, v169, v73
	v_fmac_f32_e32 v7, v169, v105
	s_waitcnt vmcnt(33)
	v_fmac_f32_e32 v10, v170, v42
	v_fmac_f32_e32 v11, v170, v74
	v_fmac_f32_e32 v7, v170, v106
	s_waitcnt vmcnt(32)
	v_fmac_f32_e32 v10, v171, v43
	v_fmac_f32_e32 v11, v171, v75
	v_fmac_f32_e32 v7, v171, v107
	s_sub_u32 s17, s17, 1
	s_cmp_lg_u32 s17, 0
	s_cbranch_scc1 .Lada_loop
	global_load_dword v140, v172, s[18:19]
	s_add_u32 s18, s18, 0xc000
	s_addc_u32 s19, s19, 0
	global_load_dword v141, v172, s[18:19]
	s_add_u32 s18, s18, 0xc000
	s_addc_u32 s19, s19, 0
	global_load_dword v142, v172, s[18:19]
	s_add_u32 s18, s18, 0xc000
	s_addc_u32 s19, s19, 0
	global_load_dword v143, v172, s[18:19]
	s_add_u32 s18, s18, 0xc000
	s_addc_u32 s19, s19, 0
	global_load_dword v144, v172, s[18:19]
	s_add_u32 s18, s18, 0xc000
	s_addc_u32 s19, s19, 0
	global_load_dword v145, v172, s[18:19]
	s_add_u32 s18, s18, 0xc000
	s_addc_u32 s19, s19, 0
	global_load_dword v146, v172, s[18:19]
	s_add_u32 s18, s18, 0xc000
	s_addc_u32 s19, s19, 0
	global_load_dword v147, v172, s[18:19]
	s_add_u32 s18, s18, 0xc000
	s_addc_u32 s19, s19, 0
	global_load_dword v148, v172, s[18:19]
	s_add_u32 s18, s18, 0xc000
	s_addc_u32 s19, s19, 0
	global_load_dword v149, v172, s[18:19]
	s_add_u32 s18, s18, 0xc000
	s_addc_u32 s19, s19, 0
	global_load_dword v150, v172, s[18:19]
	s_add_u32 s18, s18, 0xc000
	s_addc_u32 s19, s19, 0
	global_load_dword v151, v172, s[18:19]
	s_add_u32 s18, s18, 0xc000
	s_addc_u32 s19, s19, 0
	global_load_dword v152, v172, s[18:19]
	s_add_u32 s18, s18, 0xc000
	s_addc_u32 s19, s19, 0
	global_load_dword v153, v172, s[18:19]
	s_add_u32 s18, s18, 0xc000
	s_addc_u32 s19, s19, 0
	global_load_dword v154, v172, s[18:19]
	s_add_u32 s18, s18, 0xc000
	s_addc_u32 s19, s19, 0
	global_load_dword v155, v172, s[18:19]
	s_add_u32 s18, s18, 0xc000
	s_addc_u32 s19, s19, 0
	global_load_dword v156, v172, s[18:19]
	s_add_u32 s18, s18, 0xc000
	s_addc_u32 s19, s19, 0
	global_load_dword v157, v172, s[18:19]
	s_add_u32 s18, s18, 0xc000
	s_addc_u32 s19, s19, 0
	global_load_dword v158, v172, s[18:19]
	s_add_u32 s18, s18, 0xc000
	s_addc_u32 s19, s19, 0
	global_load_dword v159, v172, s[18:19]
	s_add_u32 s18, s18, 0xc000
	s_addc_u32 s19, s19, 0
	global_load_dword v160, v172, s[18:19]
	s_add_u32 s18, s18, 0xc000
	s_addc_u32 s19, s19, 0
	global_load_dword v161, v172, s[18:19]
	s_add_u32 s18, s18, 0xc000
	s_addc_u32 s19, s19, 0
	global_load_dword v162, v172, s[18:19]
	s_add_u32 s18, s18, 0xc000
	s_addc_u32 s19, s19, 0
	global_load_dword v163, v172, s[18:19]
	s_add_u32 s18, s18, 0xc000
	s_addc_u32 s19, s19, 0
	global_load_dword v164, v172, s[18:19]
	s_add_u32 s18, s18, 0xc000
	s_addc_u32 s19, s19, 0
	global_load_dword v165, v172, s[18:19]
	s_add_u32 s18, s18, 0xc000
	s_addc_u32 s19, s19, 0
	global_load_dword v166, v172, s[18:19]
	s_add_u32 s18, s18, 0xc000
	s_addc_u32 s19, s19, 0
	global_load_dword v167, v172, s[18:19]
	s_add_u32 s18, s18, 0xc000
	s_addc_u32 s19, s19, 0
	global_load_dword v168, v172, s[18:19]
	s_add_u32 s18, s18, 0xc000
	s_addc_u32 s19, s19, 0
	global_load_dword v169, v172, s[18:19]
	s_add_u32 s18, s18, 0xc000
	s_addc_u32 s19, s19, 0
	global_load_dword v170, v172, s[18:19]
	s_add_u32 s18, s18, 0xc000
	s_addc_u32 s19, s19, 0
	global_load_dword v171, v172, s[18:19]
	s_add_u32 s18, s18, 0xc000
	s_addc_u32 s19, s19, 0
	v_mov_b32_e32 v173, s15
	ds_read_b128 v[12:15], v173 offset:0
	ds_read_b128 v[16:19], v173 offset:16
	ds_read_b128 v[20:23], v173 offset:32
	ds_read_b128 v[24:27], v173 offset:48
	ds_read_b128 v[28:31], v173 offset:64
	ds_read_b128 v[32:35], v173 offset:80
	ds_read_b128 v[36:39], v173 offset:96
	ds_read_b128 v[40:43], v173 offset:112
	ds_read_b128 v[44:47], v173 offset:8192
	ds_read_b128 v[48:51], v173 offset:8208
	ds_read_b128 v[52:55], v173 offset:8224
	ds_read_b128 v[56:59], v173 offset:8240
	ds_read_b128 v[60:63], v173 offset:8256
	ds_read_b128 v[64:67], v173 offset:8272
	ds_read_b128 v[68:71], v173 offset:8288
	ds_read_b128 v[72:75], v173 offset:8304
	ds_read_b128 v[76:79], v173 offset:16384
	ds_read_b128 v[80:83], v173 offset:16400
	ds_read_b128 v[84:87], v173 offset:16416
	ds_read_b128 v[88:91], v173 offset:16432
	ds_read_b128 v[92:95], v173 offset:16448
	ds_read_b128 v[96:99], v173 offset:16464
	ds_read_b128 v[100:103], v173 offset:16480
	ds_read_b128 v[104:107], v173 offset:16496
	s_addk_i32 s15, 0x80
	s_waitcnt lgkmcnt(0)
	s_waitcnt vmcnt(63)
	v_fmac_f32_e32 v10, v108, v12
	v_fmac_f32_e32 v11, v108, v44
	v_fmac_f32_e32 v7, v108, v76
	s_waitcnt vmcnt(62)
	v_fmac_f32_e32 v10, v109, v13
	v_fmac_f32_e32 v11, v109, v45
	v_fmac_f32_e32 v7, v109, v77
	s_waitcnt vmcnt(61)
	v_fmac_f32_e32 v10, v110, v14
	v_fmac_f32_e32 v11, v110, v46
	v_fmac_f32_e32 v7, v110, v78
	s_waitcnt vmcnt(60)
	v_fmac_f32_e32 v10, v111, v15
	v_fmac_f32_e32 v11, v111, v47
	v_fmac_f32_e32 v7, v111, v79
	s_waitcnt vmcnt(59)
	v_fmac_f32_e32 v10, v112, v16
	v_fmac_f32_e32 v11, v112, v48
	v_fmac_f32_e32 v7, v112, v80
	s_waitcnt vmcnt(58)
	v_fmac_f32_e32 v10, v113, v17
	v_fmac_f32_e32 v11, v113, v49
	v_fmac_f32_e32 v7, v113, v81
	s_waitcnt vmcnt(57)
	v_fmac_f32_e32 v10, v114, v18
	v_fmac_f32_e32 v11, v114, v50
	v_fmac_f32_e32 v7, v114, v82
	s_waitcnt vmcnt(56)
	v_fmac_f32_e32 v10, v115, v19
	v_fmac_f32_e32 v11, v115, v51
	v_fmac_f32_e32 v7, v115, v83
	s_waitcnt vmcnt(55)
	v_fmac_f32_e32 v10, v116, v20
	v_fmac_f32_e32 v11, v116, v52
	v_fmac_f32_e32 v7, v116, v84
	s_waitcnt vmcnt(54)
	v_fmac_f32_e32 v10, v117, v21
	v_fmac_f32_e32 v11, v117, v53
	v_fmac_f32_e32 v7, v117, v85
	s_waitcnt vmcnt(53)
	v_fmac_f32_e32 v10, v118, v22
	v_fmac_f32_e32 v11, v118, v54
	v_fmac_f32_e32 v7, v118, v86
	s_waitcnt vmcnt(52)
	v_fmac_f32_e32 v10, v119, v23
	v_fmac_f32_e32 v11, v119, v55
	v_fmac_f32_e32 v7, v119, v87
	s_waitcnt vmcnt(51)
	v_fmac_f32_e32 v10, v120, v24
	v_fmac_f32_e32 v11, v120, v56
	v_fmac_f32_e32 v7, v120, v88
	s_waitcnt vmcnt(50)
	v_fmac_f32_e32 v10, v121, v25
	v_fmac_f32_e32 v11, v121, v57
	v_fmac_f32_e32 v7, v121, v89
	s_waitcnt vmcnt(49)
	v_fmac_f32_e32 v10, v122, v26
	v_fmac_f32_e32 v11, v122, v58
	v_fmac_f32_e32 v7, v122, v90
	s_waitcnt vmcnt(48)
	v_fmac_f32_e32 v10, v123, v27
	v_fmac_f32_e32 v11, v123, v59
	v_fmac_f32_e32 v7, v123, v91
	s_waitcnt vmcnt(47)
	v_fmac_f32_e32 v10, v124, v28
	v_fmac_f32_e32 v11, v124, v60
	v_fmac_f32_e32 v7, v124, v92
	s_waitcnt vmcnt(46)
	v_fmac_f32_e32 v10, v125, v29
	v_fmac_f32_e32 v11, v125, v61
	v_fmac_f32_e32 v7, v125, v93
	s_waitcnt vmcnt(45)
	v_fmac_f32_e32 v10, v126, v30
	v_fmac_f32_e32 v11, v126, v62
	v_fmac_f32_e32 v7, v126, v94
	s_waitcnt vmcnt(44)
	v_fmac_f32_e32 v10, v127, v31
	v_fmac_f32_e32 v11, v127, v63
	v_fmac_f32_e32 v7, v127, v95
	s_waitcnt vmcnt(43)
	v_fmac_f32_e32 v10, v128, v32
	v_fmac_f32_e32 v11, v128, v64
	v_fmac_f32_e32 v7, v128, v96
	s_waitcnt vmcnt(42)
	v_fmac_f32_e32 v10, v129, v33
	v_fmac_f32_e32 v11, v129, v65
	v_fmac_f32_e32 v7, v129, v97
	s_waitcnt vmcnt(41)
	v_fmac_f32_e32 v10, v130, v34
	v_fmac_f32_e32 v11, v130, v66
	v_fmac_f32_e32 v7, v130, v98
	s_waitcnt vmcnt(40)
	v_fmac_f32_e32 v10, v131, v35
	v_fmac_f32_e32 v11, v131, v67
	v_fmac_f32_e32 v7, v131, v99
	s_waitcnt vmcnt(39)
	v_fmac_f32_e32 v10, v132, v36
	v_fmac_f32_e32 v11, v132, v68
	v_fmac_f32_e32 v7, v132, v100
	s_waitcnt vmcnt(38)
	v_fmac_f32_e32 v10, v133, v37
	v_fmac_f32_e32 v11, v133, v69
	v_fmac_f32_e32 v7, v133, v101
	s_waitcnt vmcnt(37)
	v_fmac_f32_e32 v10, v134, v38
	v_fmac_f32_e32 v11, v134, v70
	v_fmac_f32_e32 v7, v134, v102
	s_waitcnt vmcnt(36)
	v_fmac_f32_e32 v10, v135, v39
	v_fmac_f32_e32 v11, v135, v71
	v_fmac_f32_e32 v7, v135, v103
	s_waitcnt vmcnt(35)
	v_fmac_f32_e32 v10, v136, v40
	v_fmac_f32_e32 v11, v136, v72
	v_fmac_f32_e32 v7, v136, v104
	s_waitcnt vmcnt(34)
	v_fmac_f32_e32 v10, v137, v41
	v_fmac_f32_e32 v11, v137, v73
	v_fmac_f32_e32 v7, v137, v105
	s_waitcnt vmcnt(33)
	v_fmac_f32_e32 v10, v138, v42
	v_fmac_f32_e32 v11, v138, v74
	v_fmac_f32_e32 v7, v138, v106
	s_waitcnt vmcnt(32)
	v_fmac_f32_e32 v10, v139, v43
	v_fmac_f32_e32 v11, v139, v75
	v_fmac_f32_e32 v7, v139, v107
	v_mov_b32_e32 v173, s15
	ds_read_b128 v[12:15], v173 offset:0
	ds_read_b128 v[16:19], v173 offset:16
	ds_read_b128 v[20:23], v173 offset:32
	ds_read_b128 v[24:27], v173 offset:48
	ds_read_b128 v[28:31], v173 offset:64
	ds_read_b128 v[32:35], v173 offset:80
	ds_read_b128 v[36:39], v173 offset:96
	ds_read_b128 v[40:43], v173 offset:112
	ds_read_b128 v[44:47], v173 offset:8192
	ds_read_b128 v[48:51], v173 offset:8208
	ds_read_b128 v[52:55], v173 offset:8224
	ds_read_b128 v[56:59], v173 offset:8240
	ds_read_b128 v[60:63], v173 offset:8256
	ds_read_b128 v[64:67], v173 offset:8272
	ds_read_b128 v[68:71], v173 offset:8288
	ds_read_b128 v[72:75], v173 offset:8304
	ds_read_b128 v[76:79], v173 offset:16384
	ds_read_b128 v[80:83], v173 offset:16400
	ds_read_b128 v[84:87], v173 offset:16416
	ds_read_b128 v[88:91], v173 offset:16432
	ds_read_b128 v[92:95], v173 offset:16448
	ds_read_b128 v[96:99], v173 offset:16464
	ds_read_b128 v[100:103], v173 offset:16480
	ds_read_b128 v[104:107], v173 offset:16496
	s_addk_i32 s15, 0x80
	s_waitcnt lgkmcnt(0)
	s_waitcnt vmcnt(31)
	v_fmac_f32_e32 v10, v140, v12
	v_fmac_f32_e32 v11, v140, v44
	v_fmac_f32_e32 v7, v140, v76
	s_waitcnt vmcnt(30)
	v_fmac_f32_e32 v10, v141, v13
	v_fmac_f32_e32 v11, v141, v45
	v_fmac_f32_e32 v7, v141, v77
	s_waitcnt vmcnt(29)
	v_fmac_f32_e32 v10, v142, v14
	v_fmac_f32_e32 v11, v142, v46
	v_fmac_f32_e32 v7, v142, v78
	s_waitcnt vmcnt(28)
	v_fmac_f32_e32 v10, v143, v15
	v_fmac_f32_e32 v11, v143, v47
	v_fmac_f32_e32 v7, v143, v79
	s_waitcnt vmcnt(27)
	v_fmac_f32_e32 v10, v144, v16
	v_fmac_f32_e32 v11, v144, v48
	v_fmac_f32_e32 v7, v144, v80
	s_waitcnt vmcnt(26)
	v_fmac_f32_e32 v10, v145, v17
	v_fmac_f32_e32 v11, v145, v49
	v_fmac_f32_e32 v7, v145, v81
	s_waitcnt vmcnt(25)
	v_fmac_f32_e32 v10, v146, v18
	v_fmac_f32_e32 v11, v146, v50
	v_fmac_f32_e32 v7, v146, v82
	s_waitcnt vmcnt(24)
	v_fmac_f32_e32 v10, v147, v19
	v_fmac_f32_e32 v11, v147, v51
	v_fmac_f32_e32 v7, v147, v83
	s_waitcnt vmcnt(23)
	v_fmac_f32_e32 v10, v148, v20
	v_fmac_f32_e32 v11, v148, v52
	v_fmac_f32_e32 v7, v148, v84
	s_waitcnt vmcnt(22)
	v_fmac_f32_e32 v10, v149, v21
	v_fmac_f32_e32 v11, v149, v53
	v_fmac_f32_e32 v7, v149, v85
	s_waitcnt vmcnt(21)
	v_fmac_f32_e32 v10, v150, v22
	v_fmac_f32_e32 v11, v150, v54
	v_fmac_f32_e32 v7, v150, v86
	s_waitcnt vmcnt(20)
	v_fmac_f32_e32 v10, v151, v23
	v_fmac_f32_e32 v11, v151, v55
	v_fmac_f32_e32 v7, v151, v87
	s_waitcnt vmcnt(19)
	v_fmac_f32_e32 v10, v152, v24
	v_fmac_f32_e32 v11, v152, v56
	v_fmac_f32_e32 v7, v152, v88
	s_waitcnt vmcnt(18)
	v_fmac_f32_e32 v10, v153, v25
	v_fmac_f32_e32 v11, v153, v57
	v_fmac_f32_e32 v7, v153, v89
	s_waitcnt vmcnt(17)
	v_fmac_f32_e32 v10, v154, v26
	v_fmac_f32_e32 v11, v154, v58
	v_fmac_f32_e32 v7, v154, v90
	s_waitcnt vmcnt(16)
	v_fmac_f32_e32 v10, v155, v27
	v_fmac_f32_e32 v11, v155, v59
	v_fmac_f32_e32 v7, v155, v91
	s_waitcnt vmcnt(15)
	v_fmac_f32_e32 v10, v156, v28
	v_fmac_f32_e32 v11, v156, v60
	v_fmac_f32_e32 v7, v156, v92
	s_waitcnt vmcnt(14)
	v_fmac_f32_e32 v10, v157, v29
	v_fmac_f32_e32 v11, v157, v61
	v_fmac_f32_e32 v7, v157, v93
	s_waitcnt vmcnt(13)
	v_fmac_f32_e32 v10, v158, v30
	v_fmac_f32_e32 v11, v158, v62
	v_fmac_f32_e32 v7, v158, v94
	s_waitcnt vmcnt(12)
	v_fmac_f32_e32 v10, v159, v31
	v_fmac_f32_e32 v11, v159, v63
	v_fmac_f32_e32 v7, v159, v95
	s_waitcnt vmcnt(11)
	v_fmac_f32_e32 v10, v160, v32
	v_fmac_f32_e32 v11, v160, v64
	v_fmac_f32_e32 v7, v160, v96
	s_waitcnt vmcnt(10)
	v_fmac_f32_e32 v10, v161, v33
	v_fmac_f32_e32 v11, v161, v65
	v_fmac_f32_e32 v7, v161, v97
	s_waitcnt vmcnt(9)
	v_fmac_f32_e32 v10, v162, v34
	v_fmac_f32_e32 v11, v162, v66
	v_fmac_f32_e32 v7, v162, v98
	s_waitcnt vmcnt(8)
	v_fmac_f32_e32 v10, v163, v35
	v_fmac_f32_e32 v11, v163, v67
	v_fmac_f32_e32 v7, v163, v99
	s_waitcnt vmcnt(7)
	v_fmac_f32_e32 v10, v164, v36
	v_fmac_f32_e32 v11, v164, v68
	v_fmac_f32_e32 v7, v164, v100
	s_waitcnt vmcnt(6)
	v_fmac_f32_e32 v10, v165, v37
	v_fmac_f32_e32 v11, v165, v69
	v_fmac_f32_e32 v7, v165, v101
	s_waitcnt vmcnt(5)
	v_fmac_f32_e32 v10, v166, v38
	v_fmac_f32_e32 v11, v166, v70
	v_fmac_f32_e32 v7, v166, v102
	s_waitcnt vmcnt(4)
	v_fmac_f32_e32 v10, v167, v39
	v_fmac_f32_e32 v11, v167, v71
	v_fmac_f32_e32 v7, v167, v103
	s_waitcnt vmcnt(3)
	v_fmac_f32_e32 v10, v168, v40
	v_fmac_f32_e32 v11, v168, v72
	v_fmac_f32_e32 v7, v168, v104
	s_waitcnt vmcnt(2)
	v_fmac_f32_e32 v10, v169, v41
	v_fmac_f32_e32 v11, v169, v73
	v_fmac_f32_e32 v7, v169, v105
	s_waitcnt vmcnt(1)
	v_fmac_f32_e32 v10, v170, v42
	v_fmac_f32_e32 v11, v170, v74
	v_fmac_f32_e32 v7, v170, v106
	s_waitcnt vmcnt(0)
	v_fmac_f32_e32 v10, v171, v43
	v_fmac_f32_e32 v11, v171, v75
	v_fmac_f32_e32 v7, v171, v107
	ds_write2st64_b32 v1, v10, v11 offset0:96 offset1:97
	ds_write_b32 v1, v7 offset:25088
	s_waitcnt lgkmcnt(0)
	s_barrier
	s_and_saveexec_b64 s[4:5], vcc
	s_cbranch_execz .LBB0_22
	s_load_dwordx2 s[18:19], s[8:9], 0x80
	s_ashr_i32 s17, s16, 31
	s_mul_i32 s56, s14, 0xc000
	s_mul_hi_i32 s15, s14, 0xc000
	v_mov_b64_e32 v[18:19], s[12:13]
	s_waitcnt lgkmcnt(0)
	s_add_u32 s18, s18, s56
	s_addc_u32 s15, s19, s15
	s_lshl_b64 s[16:17], s[16:17], 2
	s_add_u32 s18, s18, s16
	s_addc_u32 s19, s15, s17
	global_load_dword v7, v2, s[18:19]
	ds_read2st64_b32 v[8:9], v5 offset0:96 offset1:99
	ds_read2st64_b32 v[10:11], v5 offset0:102 offset1:105
	ds_read2st64_b32 v[12:13], v5 offset0:108 offset1:111
	ds_read2st64_b32 v[14:15], v5 offset0:114 offset1:117
	v_mad_u64_u32 v[16:17], s[14:15], s14, 3, v[0:1]
	v_mad_i64_i32 v[16:17], s[14:15], v16, s23, v[18:19]
	v_lshl_add_u64 v[16:17], v[16:17], 0, s[16:17]
	s_waitcnt vmcnt(0) lgkmcnt(3)
	v_add_f32_e32 v7, v7, v8
	v_add_f32_e32 v7, v7, v9
	s_waitcnt lgkmcnt(2)
	v_add_f32_e32 v7, v7, v10
	v_add_f32_e32 v7, v7, v11
	s_waitcnt lgkmcnt(1)
	v_add_f32_e32 v7, v7, v12
	v_add_f32_e32 v7, v7, v13
	s_waitcnt lgkmcnt(0)
	v_add_f32_e32 v7, v7, v14
	v_add_f32_e32 v7, v7, v15
	v_lshl_add_u64 v[8:9], v[16:17], 0, v[2:3]
	global_store_dword v[8:9], v7, off
	s_branch .LBB0_22
